# attention phase B in-loop register-stage loads: 3 VALU per K/V pair (v_med3 clamp, shift-add, SGPR-base addressing) instead of 11
# speedup vs baseline: 1.0017x; 1.0017x over previous
.Lrl_do1:
	s_cmp_eq_u32 s75, 1
	s_cselect_b32 s0, 2, 4
	s_lshr_b32 s16, s8, s0
	s_lshl_b32 s17, s76, 6
	s_lshr_b32 s1, 0x800, s0
	s_add_i32 s16, s16, s17
	s_add_i32 s1, s1, -1
	s_lshl_b32 s20, -1, s0
	s_andn2_b32 s20, s8, s20
	s_lshl_b32 s98, s20, 7
	s_add_i32 s99, s0, 7
	v_add_u32_e32 v251, s16, v191
	v_add_u32_e32 v250, s98, v184
	s_mov_b64 s[16:17], 0
	s_waitcnt lgkmcnt(0)
	v_med3_i32 v2, v251, 0, s1
	v_lshl_add_u32 v2, v2, s99, v250
	global_load_dwordx4 v[4:7], v2, s[10:11]
	global_load_dwordx4 v[12:15], v2, s[12:13]
	v_add_u32_e32 v3, 8, v251
	v_med3_i32 v3, v3, 0, s1
	v_lshl_add_u32 v3, v3, s99, v250
	global_load_dwordx4 v[8:11], v3, s[10:11]
	global_load_dwordx4 v[24:27], v3, s[12:13]
	s_cmp_lg_u32 s75, 2
	s_cbranch_scc1 .Lrl_full1
	s_waitcnt lgkmcnt(0)
	s_cmp_eq_u32 s76, 2
	s_cbranch_scc1 .Lrl_tail1
.Lrl_full1:
	v_add_u32_e32 v2, 16, v251
	v_med3_i32 v2, v2, 0, s1
	v_lshl_add_u32 v2, v2, s99, v250
	global_load_dwordx4 v[16:19], v2, s[10:11]
	global_load_dwordx4 v[32:35], v2, s[12:13]
	v_add_u32_e32 v3, 24, v251
	v_med3_i32 v3, v3, 0, s1
	v_lshl_add_u32 v3, v3, s99, v250
	global_load_dwordx4 v[20:23], v3, s[10:11]
	global_load_dwordx4 v[40:43], v3, s[12:13]
	v_add_u32_e32 v2, 32, v251
	v_med3_i32 v2, v2, 0, s1
	v_lshl_add_u32 v2, v2, s99, v250
	global_load_dwordx4 v[28:31], v2, s[10:11]
	global_load_dwordx4 v[52:55], v2, s[12:13]
	v_add_u32_e32 v3, 40, v251
	v_med3_i32 v3, v3, 0, s1
	v_lshl_add_u32 v3, v3, s99, v250
	global_load_dwordx4 v[36:39], v3, s[10:11]
	global_load_dwordx4 v[64:67], v3, s[12:13]
	v_add_u32_e32 v2, 48, v251
	v_med3_i32 v2, v2, 0, s1
	v_lshl_add_u32 v2, v2, s99, v250
	global_load_dwordx4 v[44:47], v2, s[10:11]
	global_load_dwordx4 v[76:79], v2, s[12:13]
	v_add_u32_e32 v3, 56, v251
	v_med3_i32 v3, v3, 0, s1
	v_lshl_add_u32 v3, v3, s99, v250
	global_load_dwordx4 v[68:71], v3, s[10:11]
	global_load_dwordx4 v[88:91], v3, s[12:13]

.Lrl_do2:
	s_cmp_eq_u32 s75, 1
	s_cselect_b32 s0, 2, 4
	s_lshr_b32 s14, s8, s0
	s_lshl_b32 s15, s76, 6
	s_lshr_b32 s1, 0x800, s0
	s_add_i32 s14, s14, s15
	s_add_i32 s1, s1, -1
	s_lshl_b32 s20, -1, s0
	s_andn2_b32 s20, s8, s20
	s_lshl_b32 s98, s20, 7
	s_add_i32 s99, s0, 7
	v_add_u32_e32 v251, s14, v191
	v_add_u32_e32 v250, s98, v184
	s_waitcnt lgkmcnt(0)
	v_med3_i32 v2, v251, 0, s1
	v_lshl_add_u32 v2, v2, s99, v250
	global_load_dwordx4 v[56:59], v2, s[10:11]
	global_load_dwordx4 v[48:51], v2, s[12:13]
	v_add_u32_e32 v3, 8, v251
	v_med3_i32 v3, v3, 0, s1
	v_lshl_add_u32 v3, v3, s99, v250
	global_load_dwordx4 v[72:75], v3, s[10:11]
	global_load_dwordx4 v[60:63], v3, s[12:13]
	s_cmp_lg_u32 s75, 2
	s_cbranch_scc1 .Lrl_full2
	s_waitcnt lgkmcnt(0)
	s_cmp_eq_u32 s76, 2
	s_cbranch_scc1 .Lrl_tail2
.Lrl_full2:
	v_add_u32_e32 v2, 16, v251
	v_med3_i32 v2, v2, 0, s1
	v_lshl_add_u32 v2, v2, s99, v250
	global_load_dwordx4 v[84:87], v2, s[10:11]
	global_load_dwordx4 v[80:83], v2, s[12:13]
	v_add_u32_e32 v3, 24, v251
	v_med3_i32 v3, v3, 0, s1
	v_lshl_add_u32 v3, v3, s99, v250
	global_load_dwordx4 v[96:99], v3, s[10:11]
	global_load_dwordx4 v[92:95], v3, s[12:13]
	v_add_u32_e32 v2, 32, v251
	v_med3_i32 v2, v2, 0, s1
	v_lshl_add_u32 v2, v2, s99, v250
	global_load_dwordx4 v[104:107], v2, s[10:11]
	global_load_dwordx4 v[100:103], v2, s[12:13]
	v_add_u32_e32 v3, 40, v251
	v_med3_i32 v3, v3, 0, s1
	v_lshl_add_u32 v3, v3, s99, v250
	global_load_dwordx4 v[112:115], v3, s[10:11]
	global_load_dwordx4 v[108:111], v3, s[12:13]
	v_add_u32_e32 v2, 48, v251
	v_med3_i32 v2, v2, 0, s1
	v_lshl_add_u32 v2, v2, s99, v250
	global_load_dwordx4 v[120:123], v2, s[10:11]
	global_load_dwordx4 v[116:119], v2, s[12:13]
	v_add_u32_e32 v3, 56, v251
	v_med3_i32 v3, v3, 0, s1
	v_lshl_add_u32 v3, v3, s99, v250
	global_load_dwordx4 v[128:131], v3, s[10:11]
	global_load_dwordx4 v[124:127], v3, s[12:13]
